# v27 = v22 + attention unit prologue: K3/V1 DMA, K1 fragment reads and step-0 exps moved before the post-step-0 barrier (vmcnt(0) -> vmcnt(3))
# speedup vs baseline: 1.0037x; 1.0011x over previous
.LBB0_567:
	s_add_u32 s48, s64, 0x6c000
	s_addc_u32 s49, s65, 0
	s_cmp_lg_u32 0, -1
	s_cselect_b32 s60, 0, 0
	s_add_i32 s60, s60, s73
	s_add_i32 s60, s60, 0x9000
	s_mov_b32 m0, s60
	s_nop 0
	global_load_lds_dwordx4 v183, s[48:49]
	s_and_saveexec_b64 s[48:49], s[2:3]
	s_cbranch_execz .LBB0_569
	s_add_u32 s60, s46, 0x3000
	s_addc_u32 s61, s47, 0
	s_add_i32 s66, s76, 0x9000
	s_mov_b32 m0, s66
	s_nop 0
	global_load_lds_dwordx4 v184, s[60:61]
.LBB0_569:
	s_or_b64 exec, exec, s[48:49]
	s_add_i32 s48, s81, 0x100
	s_lshr_b32 s80, s48, 6
	s_add_u32 s66, s8, 0x18000
	s_addc_u32 s67, s9, 0
	s_cmp_lg_u32 0, -1
	s_cselect_b32 s48, 0, 0
	s_add_i32 s48, s48, s73
	s_add_i32 s48, s48, 0xe000
	s_mov_b32 m0, s48
	s_nop 0
	global_load_lds_dwordx4 v185, s[66:67]
	ds_read_b128 v[80:83], v179 offset:12288
	ds_read_b128 v[136:139], v179 offset:12800
	ds_read_b128 v[140:143], v179 offset:14336
	v_exp_f32_e32 v48, v16
	v_exp_f32_e32 v49, v17
	v_exp_f32_e32 v50, v18
	v_exp_f32_e32 v51, v19
	v_exp_f32_e32 v52, v20
	v_exp_f32_e32 v53, v21
	v_exp_f32_e32 v54, v22
	v_exp_f32_e32 v55, v23
	v_exp_f32_e32 v56, v24
	v_exp_f32_e32 v57, v25
	v_exp_f32_e32 v58, v26
	v_exp_f32_e32 v59, v27
	v_exp_f32_e32 v60, v28
	v_exp_f32_e32 v61, v29
	v_exp_f32_e32 v62, v30
	v_exp_f32_e32 v63, v31
	v_exp_f32_e32 v32, v0
	v_exp_f32_e32 v33, v1
	v_exp_f32_e32 v34, v2
	v_exp_f32_e32 v35, v3
	v_exp_f32_e32 v36, v4
	v_exp_f32_e32 v37, v5
	v_exp_f32_e32 v38, v6
	v_exp_f32_e32 v39, v7
	v_exp_f32_e32 v40, v8
	v_exp_f32_e32 v41, v9
	v_exp_f32_e32 v42, v10
	v_exp_f32_e32 v43, v11
	v_exp_f32_e32 v44, v12
	v_exp_f32_e32 v45, v13
	v_exp_f32_e32 v46, v14
	v_exp_f32_e32 v47, v15
	s_waitcnt vmcnt(3) lgkmcnt(0)
	s_barrier
	s_mov_b32 s86, 0
	s_andn2_b64 vcc, exec, s[0:1]
	s_mov_b32 s0, 1
	s_cbranch_vccnz .LBB0_595
	s_add_u32 s68, s8, 0x48000
	s_addc_u32 s69, s9, 0
	s_add_u32 s48, s64, 0xb4000
	s_addc_u32 s49, s65, 0
	v_mov_b32_e32 v16, v153
	v_mov_b32_e32 v17, v153
	s_add_u32 s8, s46, 0x5000
	v_mov_b32_e32 v18, v153
	v_mov_b32_e32 v19, v153
	v_mov_b32_e32 v20, v153
	v_mov_b32_e32 v21, v153
	v_mov_b32_e32 v22, v153
	v_mov_b32_e32 v23, v153
	v_mov_b32_e32 v24, v153
	v_mov_b32_e32 v25, v153
	v_mov_b32_e32 v26, v153
	v_mov_b32_e32 v27, v153
	v_mov_b32_e32 v28, v153
	v_mov_b32_e32 v29, v153
	v_mov_b32_e32 v30, v153
	v_mov_b32_e32 v31, v153
	v_mov_b64_e32 v[0:1], v[16:17]
	s_addc_u32 s9, s47, 0
	s_mov_b32 s0, 0
	s_movk_i32 s83, 0x6000
	s_movk_i32 s82, 0x3000
	s_movk_i32 s86, 0x4000
	s_movk_i32 s79, 0x2000
	s_mov_b64 s[60:61], 0
	v_mov_b32_e32 v166, 0
	s_mov_b32 s87, 6
	v_mov_b64_e32 v[2:3], v[18:19]
	v_mov_b64_e32 v[4:5], v[20:21]
	v_mov_b64_e32 v[6:7], v[22:23]
	v_mov_b64_e32 v[8:9], v[24:25]
	v_mov_b64_e32 v[10:11], v[26:27]
	v_mov_b64_e32 v[12:13], v[28:29]
	v_mov_b64_e32 v[14:15], v[30:31]
	s_mov_b32 s84, 0
